# phase_ya also walks its tiles in reverse so the merge phase reads the freshest rows first
# baseline (speedup 1.0000x reference)
; DI void phase_ya(const Params& p, int l, int L, const bf16_t* __restrict__ sg, const bf16_t* __restrict__ g2t, const bf16_t* __restrict__ z,
;                  bf16_t* __restrict__ yf, const bf16_t* __restrict__ yb, const float* __restrict__ bon, unsigned char* smem) {
;     ...
;   for (int id = blockIdx.x; id < nM * nN; id += gridDim.x) {
;     int pm, pn; tile_coords(id, nN, pm, pn);
;     f32x4 acc[4][4]; zero_acc(acc);
;     {
;       const int idn = id + gridDim.x; int pm2 = 0, pn2 = 0; const bool hn = idn < nM * nN; if (hn) tile_coords(idn, nN, pm2, pn2);
;       gemm_block<4, 4, 4, 2>(sg + (size_t)pm * 256 * 128, 128, g2t + (size_t)pn * 128 * 128, 128, 128, acc, smem, id != (int)blockIdx.x,
;                              hn ? sg + (size_t)pm2 * 256 * 128 : nullptr, 128, g2t + (size_t)pn2 * 128 * 128, 128);
.LBB0_582:
	v_readlane_b32 s2, v253, 37
	s_add_i32 s2, s2, s51
	s_cmpk_gt_i32 s2, 0x3ff
	s_cselect_b64 s[10:11], -1, 0
	s_cmpk_lt_i32 s2, 0x400
	s_cselect_b64 s[14:15], -1, 0
	s_mov_b64 s[16:17], 0
	s_and_b64 vcc, exec, s[10:11]
	s_mov_b64 s[42:43], 0
	s_cbranch_vccnz .LBB0_584
	s_xor_b32 s99, s2, 0x3ff
	s_ashr_i32 s6, s99, 31
	s_lshr_b32 s6, s6, 26
	s_add_i32 s6, s99, s6
	s_ashr_i32 s7, s6, 6
	s_andn2_b32 s6, s6, 63
	s_sub_i32 s2, s99, s6
	s_lshl_b32 s6, s7, 4
	s_and_b32 s7, s2, 15
	s_or_b32 s6, s7, s6
	s_ashr_i32 s12, s2, 4
	s_ashr_i32 s7, s6, 31
	s_ashr_i32 s13, s12, 31
	s_lshl_b64 s[16:17], s[6:7], 16
	s_lshl_b64 s[42:43], s[12:13], 15
.LBB0_584:
	s_add_i32 s2, s92, s51
	s_xor_b32 s99, s2, 0x3ff
	s_ashr_i32 s6, s99, 31
	s_lshr_b32 s6, s6, 26
	s_add_i32 s6, s99, s6
	s_ashr_i32 s7, s6, 6
	s_andn2_b32 s6, s6, 63
	s_sub_i32 s2, s99, s6
	s_lshl_b32 s6, s7, 4
	s_and_b32 s7, s2, 15
	s_or_b32 s6, s7, s6
	s_ashr_i32 s7, s6, 31
	s_ashr_i32 s12, s2, 4
	s_lshl_b64 s[18:19], s[6:7], 16
	v_readlane_b32 s20, v253, 25
	v_readlane_b32 s21, v253, 26
	s_add_u32 s18, s20, s18
	s_addc_u32 s19, s21, s19
	s_ashr_i32 s13, s12, 31
	s_lshl_b64 s[20:21], s[12:13], 15
	s_add_u32 s20, s8, s20
	s_addc_u32 s21, s50, s21
	v_mov_b32_e32 v5, v212
	s_cmp_eq_u32 s51, 0
	s_nop 0
	v_lshlrev_b32_e32 v6, 4, v5
	s_cbranch_scc1 .LBB0_586
	v_lshlrev_b32_e32 v64, 4, v5
	s_mov_b64 s[22:23], 0
	s_branch .LBB0_587
